# gemm_phase: post-epilogue vmcnt(0) relaxed to vmcnt(8) so the epilogue stores drain under the next unit's K loop
# speedup vs baseline: 1.0096x; 1.0096x over previous
; #define PG8_BAR __builtin_amdgcn_s_barrier()
; DI void gemm_phase(LAS unsigned char* lds, const GemmD g, const int kind, const int l) {
;     ...
;         if (wr == 0) PG8_BAR;
;         epilogue(kind, l, acc, cur, wr, wc, fr, fq);
;         __builtin_amdgcn_s_waitcnt(0x0F70);
;         if (!has_next) break;
; #pragma unroll
;         for (int a = 0; a < 2; ++a)
; #pragma unroll
;             for (int b = 0; b < 2; ++b)
; #pragma unroll
;                 for (int m = 0; m < 4; ++m)
; #pragma unroll
;                     for (int n = 0; n < 2; ++n) acc[a][b][m][n] = (f32x4){0.f, 0.f, 0.f, 0.f};
;         cur = nxt; cA = nA; cB = nB; ++ui;
;         if (wr == 1) PG8_BAR;
;     }
.LBB0_813:
	s_and_b64 vcc, exec, s[40:41]
	s_mov_b64 s[4:5], -1
	s_mov_b32 s90, 0x20a61000
	s_movk_i32 s91, 0x3000
	s_movk_i32 s92, 0x2000
	s_movk_i32 s93, 0x7f0
	s_waitcnt lgkmcnt(0)
	s_movk_i32 s94, 0x3fff
	s_mov_b32 s95, s69
	s_mov_b64 s[96:97], 0x1400
	s_waitcnt vmcnt(8)
	s_cbranch_vccnz .LBB0_242
	v_readlane_b32 s4, v255, 41
	v_readlane_b32 s5, v255, 42
	s_andn2_b64 vcc, exec, s[4:5]
	s_cbranch_vccnz .LBB0_241
	s_barrier
	s_branch .LBB0_241
